# opt14 + G6 EpiResid epilogue regenerated the same way (loads two row groups ahead, SGPR-base addressing, counted vmcnt)
# baseline (speedup 1.0000x reference)
; __device__ __forceinline__ unsigned cvt_pk_bf16(float lo, float hi) { f32x2_t v = {lo, hi}; bf16x2_t b = __builtin_convertvector(v, bf16x2_t); return __builtin_bit_cast(unsigned, b); }
;     __device__ __forceinline__ void operator()(const Acc& acc, const Unit& u, int wr, int wc, int fr, int fq) const {
;         const int row0 = u.pm * BM + wr * 64 + fr, col0 = u.pn * BM + wc * 32 + 8 * fq;
; #pragma unroll
;         for (int ai = 0; ai < 2; ++ai)
; #pragma unroll
;             for (int m = 0; m < 4; ++m) {
;                 const int row = row0 + ai * HALF + m * 16; float sq = 0.f;
; #pragma unroll
;                 for (int bj = 0; bj < 2; ++bj) {
;                     const size_t off = (size_t)row * DM + col0 + bj * HALF;
;                     const f32x4 b0 = *(const f32x4*)(base + off), b1 = *(const f32x4*)(base + off + 4);
;                     const f32x4 x0 = b0 + acc[ai][bj][m][0] * alpha, x1 = b1 + acc[ai][bj][m][1] * alpha;
;                     __builtin_nontemporal_store(x0, (f32x4*)(out + off)); __builtin_nontemporal_store(x1, (f32x4*)(out + off + 4));
;                     sq += (x0[0] * x0[0] + x0[1] * x0[1]) + (x0[2] * x0[2] + x0[3] * x0[3]) + (x1[0] * x1[0] + x1[1] * x1[1]) + (x1[2] * x1[2] + x1[3] * x1[3]);
;                     if (xb) { u32x4 w; w.x = cvt_pk_bf16(x0[0], x0[1]); w.y = cvt_pk_bf16(x0[2], x0[3]); w.z = cvt_pk_bf16(x1[0], x1[1]); w.w = cvt_pk_bf16(x1[2], x1[3]); *(u32x4*)(xb + off) = w; }
;                 }
;                 sq += __shfl_xor(sq, 16); sq += __shfl_xor(sq, 32);
;                 if (fq == 0) unsafeAtomicAdd(ss + row, sq);
;             }
.LBB0_1237:
	s_and_b64 vcc, exec, s[36:37]
	s_cbranch_vccz .Lg6_epi_old
	v_lshl_add_u32 v146, s12, 8, v152
	v_lshl_or_b32 v144, s46, 8, v154
	v_lshl_add_u32 v145, v146, 10, v144
	v_lshlrev_b32_e32 v144, 2, v145
	v_lshlrev_b32_e32 v145, 1, v145
	v_lshlrev_b32_e32 v146, 2, v146
	v_mbcnt_lo_u32_b32 v149, -1, 0
	v_mbcnt_hi_u32_b32 v149, -1, v149
	v_xor_b32_e32 v147, 16, v149
	v_lshlrev_b32_e32 v147, 2, v147
	v_xor_b32_e32 v148, 32, v149
	v_lshlrev_b32_e32 v148, 2, v148
	s_mov_b64 s[84:85], s[82:83]
	global_load_dwordx4 v[184:187], v144, s[84:85]
	global_load_dwordx4 v[188:191], v144, s[84:85] offset:16
	global_load_dwordx4 v[192:195], v144, s[84:85] offset:512
	global_load_dwordx4 v[196:199], v144, s[84:85] offset:528
	s_add_u32 s84, s82, 0x10000
	s_addc_u32 s85, s83, 0
	global_load_dwordx4 v[200:203], v144, s[84:85]
	global_load_dwordx4 v[204:207], v144, s[84:85] offset:16
	global_load_dwordx4 v[208:211], v144, s[84:85] offset:512
	global_load_dwordx4 v[212:215], v144, s[84:85] offset:528
	s_waitcnt vmcnt(4)
	v_fma_f32 v124, v124, 1.0, v184
	v_fma_f32 v125, v125, 1.0, v185
	v_fma_f32 v126, v126, 1.0, v186
	v_fma_f32 v127, v127, 1.0, v187
	v_fma_f32 v120, v120, 1.0, v188
	v_fma_f32 v121, v121, 1.0, v189
	v_fma_f32 v122, v122, 1.0, v190
	v_fma_f32 v123, v123, 1.0, v191
	v_fma_f32 v116, v116, 1.0, v192
	v_fma_f32 v117, v117, 1.0, v193
	v_fma_f32 v118, v118, 1.0, v194
	v_fma_f32 v119, v119, 1.0, v195
	v_fma_f32 v112, v112, 1.0, v196
	v_fma_f32 v113, v113, 1.0, v197
	v_fma_f32 v114, v114, 1.0, v198
	v_fma_f32 v115, v115, 1.0, v199
	s_add_u32 s84, s82, 0x20000
	s_addc_u32 s85, s83, 0
	global_load_dwordx4 v[216:219], v144, s[84:85]
	global_load_dwordx4 v[220:223], v144, s[84:85] offset:16
	global_load_dwordx4 v[224:227], v144, s[84:85] offset:512
	global_load_dwordx4 v[228:231], v144, s[84:85] offset:528
	s_mov_b64 s[86:87], s[82:83]
	global_store_dwordx4 v144, v[124:127], s[86:87] nt
	global_store_dwordx4 v144, v[120:123], s[86:87] offset:16 nt
	global_store_dwordx4 v144, v[116:119], s[86:87] offset:512 nt
	global_store_dwordx4 v144, v[112:115], s[86:87] offset:528 nt
	v_cvt_pk_bf16_f32 v236, v124, v125
	v_cvt_pk_bf16_f32 v237, v126, v127
	v_cvt_pk_bf16_f32 v238, v120, v121
	v_cvt_pk_bf16_f32 v239, v122, v123
	v_cvt_pk_bf16_f32 v240, v116, v117
	v_cvt_pk_bf16_f32 v241, v118, v119
	v_cvt_pk_bf16_f32 v242, v112, v113
	v_cvt_pk_bf16_f32 v243, v114, v115
	s_mov_b64 s[88:89], s[72:73]
	global_store_dwordx4 v145, v[236:239], s[88:89]
	global_store_dwordx4 v145, v[240:243], s[88:89] offset:256
	v_mul_f32_e32 v232, v125, v125
	v_fmac_f32_e32 v232, v124, v124
	v_mul_f32_e32 v233, v121, v121
	v_fmac_f32_e32 v233, v120, v120
	v_mul_f32_e32 v234, v117, v117
	v_fmac_f32_e32 v234, v116, v116
	v_mul_f32_e32 v235, v113, v113
	v_fmac_f32_e32 v235, v112, v112
	v_mul_f32_e32 v248, v127, v127
	v_fmac_f32_e32 v248, v126, v126
	v_mul_f32_e32 v249, v123, v123
	v_fmac_f32_e32 v249, v122, v122
	v_mul_f32_e32 v250, v119, v119
	v_fmac_f32_e32 v250, v118, v118
	v_mul_f32_e32 v251, v115, v115
	v_fmac_f32_e32 v251, v114, v114
	v_add_f32_e32 v232, v232, v248
	v_add_f32_e32 v233, v233, v249
	v_add_f32_e32 v234, v234, v250
	v_add_f32_e32 v235, v235, v251
	v_add_f32_e32 v232, v232, v233
	v_add_f32_e32 v234, v234, v235
	v_add_f32_e32 v232, v232, v234
	ds_bpermute_b32 v233, v147, v232
	s_waitcnt lgkmcnt(0)
	v_add_f32_e32 v232, v232, v233
	ds_bpermute_b32 v233, v148, v232
	s_waitcnt lgkmcnt(0)
	v_add_f32_e32 v232, v232, v233
	s_and_saveexec_b64 s[6:7], s[8:9]
	global_atomic_add_f32 v146, v232, s[2:3]
	s_mov_b64 exec, s[6:7]
	s_waitcnt vmcnt(11)
	v_fma_f32 v108, v108, 1.0, v200
	v_fma_f32 v109, v109, 1.0, v201
	v_fma_f32 v110, v110, 1.0, v202
	v_fma_f32 v111, v111, 1.0, v203
	v_fma_f32 v104, v104, 1.0, v204
	v_fma_f32 v105, v105, 1.0, v205
	v_fma_f32 v106, v106, 1.0, v206
	v_fma_f32 v107, v107, 1.0, v207
	v_fma_f32 v100, v100, 1.0, v208
	v_fma_f32 v101, v101, 1.0, v209
	v_fma_f32 v102, v102, 1.0, v210
	v_fma_f32 v103, v103, 1.0, v211
	v_fma_f32 v96, v96, 1.0, v212
	v_fma_f32 v97, v97, 1.0, v213
	v_fma_f32 v98, v98, 1.0, v214
	v_fma_f32 v99, v99, 1.0, v215
	s_add_u32 s84, s82, 0x30000
	s_addc_u32 s85, s83, 0
	global_load_dwordx4 v[184:187], v144, s[84:85]
	global_load_dwordx4 v[188:191], v144, s[84:85] offset:16
	global_load_dwordx4 v[192:195], v144, s[84:85] offset:512
	global_load_dwordx4 v[196:199], v144, s[84:85] offset:528
	s_add_u32 s86, s82, 0x10000
	s_addc_u32 s87, s83, 0
	global_store_dwordx4 v144, v[108:111], s[86:87] nt
	global_store_dwordx4 v144, v[104:107], s[86:87] offset:16 nt
	global_store_dwordx4 v144, v[100:103], s[86:87] offset:512 nt
	global_store_dwordx4 v144, v[96:99], s[86:87] offset:528 nt
	v_cvt_pk_bf16_f32 v236, v108, v109
	v_cvt_pk_bf16_f32 v237, v110, v111
	v_cvt_pk_bf16_f32 v238, v104, v105
	v_cvt_pk_bf16_f32 v239, v106, v107
	v_cvt_pk_bf16_f32 v240, v100, v101
	v_cvt_pk_bf16_f32 v241, v102, v103
	v_cvt_pk_bf16_f32 v242, v96, v97
	v_cvt_pk_bf16_f32 v243, v98, v99
	s_add_u32 s88, s72, 0x8000
	s_addc_u32 s89, s73, 0
	global_store_dwordx4 v145, v[236:239], s[88:89]
	global_store_dwordx4 v145, v[240:243], s[88:89] offset:256
	v_mul_f32_e32 v232, v109, v109
	v_fmac_f32_e32 v232, v108, v108
	v_mul_f32_e32 v233, v105, v105
	v_fmac_f32_e32 v233, v104, v104
	v_mul_f32_e32 v234, v101, v101
	v_fmac_f32_e32 v234, v100, v100
	v_mul_f32_e32 v235, v97, v97
	v_fmac_f32_e32 v235, v96, v96
	v_mul_f32_e32 v248, v111, v111
	v_fmac_f32_e32 v248, v110, v110
	v_mul_f32_e32 v249, v107, v107
	v_fmac_f32_e32 v249, v106, v106
	v_mul_f32_e32 v250, v103, v103
	v_fmac_f32_e32 v250, v102, v102
	v_mul_f32_e32 v251, v99, v99
	v_fmac_f32_e32 v251, v98, v98
	v_add_f32_e32 v232, v232, v248
	v_add_f32_e32 v233, v233, v249
	v_add_f32_e32 v234, v234, v250
	v_add_f32_e32 v235, v235, v251
	v_add_f32_e32 v232, v232, v233
	v_add_f32_e32 v234, v234, v235
	v_add_f32_e32 v232, v232, v234
	ds_bpermute_b32 v233, v147, v232
	s_waitcnt lgkmcnt(0)
; __device__ __forceinline__ unsigned cvt_pk_bf16(float lo, float hi) { f32x2_t v = {lo, hi}; bf16x2_t b = __builtin_convertvector(v, bf16x2_t); return __builtin_bit_cast(unsigned, b); }
;     __device__ __forceinline__ void operator()(const Acc& acc, const Unit& u, int wr, int wc, int fr, int fq) const {
;         const int row0 = u.pm * BM + wr * 64 + fr, col0 = u.pn * BM + wc * 32 + 8 * fq;
; #pragma unroll
;         for (int ai = 0; ai < 2; ++ai)
; #pragma unroll
;             for (int m = 0; m < 4; ++m) {
;                 const int row = row0 + ai * HALF + m * 16; float sq = 0.f;
; #pragma unroll
;                 for (int bj = 0; bj < 2; ++bj) {
;                     const size_t off = (size_t)row * DM + col0 + bj * HALF;
;                     const f32x4 b0 = *(const f32x4*)(base + off), b1 = *(const f32x4*)(base + off + 4);
;                     const f32x4 x0 = b0 + acc[ai][bj][m][0] * alpha, x1 = b1 + acc[ai][bj][m][1] * alpha;
;                     __builtin_nontemporal_store(x0, (f32x4*)(out + off)); __builtin_nontemporal_store(x1, (f32x4*)(out + off + 4));
;                     sq += (x0[0] * x0[0] + x0[1] * x0[1]) + (x0[2] * x0[2] + x0[3] * x0[3]) + (x1[0] * x1[0] + x1[1] * x1[1]) + (x1[2] * x1[2] + x1[3] * x1[3]);
;                     if (xb) { u32x4 w; w.x = cvt_pk_bf16(x0[0], x0[1]); w.y = cvt_pk_bf16(x0[2], x0[3]); w.z = cvt_pk_bf16(x1[0], x1[1]); w.w = cvt_pk_bf16(x1[2], x1[3]); *(u32x4*)(xb + off) = w; }
;                 }
;                 sq += __shfl_xor(sq, 16); sq += __shfl_xor(sq, 32);
;                 if (fq == 0) unsafeAtomicAdd(ss + row, sq);
;             }
	v_add_f32_e32 v232, v232, v233
	ds_bpermute_b32 v233, v148, v232
	s_waitcnt lgkmcnt(0)
	v_add_f32_e32 v232, v232, v233
	s_and_saveexec_b64 s[6:7], s[8:9]
	global_atomic_add_f32 v146, v232, s[2:3] offset:64
	s_mov_b64 exec, s[6:7]
	s_waitcnt vmcnt(18)
	v_fma_f32 v92, v92, 1.0, v216
	v_fma_f32 v93, v93, 1.0, v217
	v_fma_f32 v94, v94, 1.0, v218
	v_fma_f32 v95, v95, 1.0, v219
	v_fma_f32 v88, v88, 1.0, v220
	v_fma_f32 v89, v89, 1.0, v221
	v_fma_f32 v90, v90, 1.0, v222
	v_fma_f32 v91, v91, 1.0, v223
	v_fma_f32 v84, v84, 1.0, v224
	v_fma_f32 v85, v85, 1.0, v225
	v_fma_f32 v86, v86, 1.0, v226
	v_fma_f32 v87, v87, 1.0, v227
	v_fma_f32 v80, v80, 1.0, v228
	v_fma_f32 v81, v81, 1.0, v229
	v_fma_f32 v82, v82, 1.0, v230
	v_fma_f32 v83, v83, 1.0, v231
	s_add_u32 s84, s82, 0x80000
	s_addc_u32 s85, s83, 0
	global_load_dwordx4 v[200:203], v144, s[84:85]
	global_load_dwordx4 v[204:207], v144, s[84:85] offset:16
	global_load_dwordx4 v[208:211], v144, s[84:85] offset:512
	global_load_dwordx4 v[212:215], v144, s[84:85] offset:528
	s_add_u32 s86, s82, 0x20000
	s_addc_u32 s87, s83, 0
	global_store_dwordx4 v144, v[92:95], s[86:87] nt
	global_store_dwordx4 v144, v[88:91], s[86:87] offset:16 nt
	global_store_dwordx4 v144, v[84:87], s[86:87] offset:512 nt
	global_store_dwordx4 v144, v[80:83], s[86:87] offset:528 nt
	v_cvt_pk_bf16_f32 v236, v92, v93
	v_cvt_pk_bf16_f32 v237, v94, v95
	v_cvt_pk_bf16_f32 v238, v88, v89
	v_cvt_pk_bf16_f32 v239, v90, v91
	v_cvt_pk_bf16_f32 v240, v84, v85
	v_cvt_pk_bf16_f32 v241, v86, v87
	v_cvt_pk_bf16_f32 v242, v80, v81
	v_cvt_pk_bf16_f32 v243, v82, v83
	s_add_u32 s88, s72, 0x10000
	s_addc_u32 s89, s73, 0
	global_store_dwordx4 v145, v[236:239], s[88:89]
	global_store_dwordx4 v145, v[240:243], s[88:89] offset:256
	v_mul_f32_e32 v232, v93, v93
	v_fmac_f32_e32 v232, v92, v92
	v_mul_f32_e32 v233, v89, v89
	v_fmac_f32_e32 v233, v88, v88
	v_mul_f32_e32 v234, v85, v85
	v_fmac_f32_e32 v234, v84, v84
	v_mul_f32_e32 v235, v81, v81
	v_fmac_f32_e32 v235, v80, v80
	v_mul_f32_e32 v248, v95, v95
	v_fmac_f32_e32 v248, v94, v94
	v_mul_f32_e32 v249, v91, v91
	v_fmac_f32_e32 v249, v90, v90
	v_mul_f32_e32 v250, v87, v87
	v_fmac_f32_e32 v250, v86, v86
	v_mul_f32_e32 v251, v83, v83
	v_fmac_f32_e32 v251, v82, v82
	v_add_f32_e32 v232, v232, v248
	v_add_f32_e32 v233, v233, v249
	v_add_f32_e32 v234, v234, v250
	v_add_f32_e32 v235, v235, v251
	v_add_f32_e32 v232, v232, v233
	v_add_f32_e32 v234, v234, v235
	v_add_f32_e32 v232, v232, v234
	ds_bpermute_b32 v233, v147, v232
	s_waitcnt lgkmcnt(0)
	v_add_f32_e32 v232, v232, v233
	ds_bpermute_b32 v233, v148, v232
	s_waitcnt lgkmcnt(0)
	v_add_f32_e32 v232, v232, v233
	s_and_saveexec_b64 s[6:7], s[8:9]
	global_atomic_add_f32 v146, v232, s[2:3] offset:128
	s_mov_b64 exec, s[6:7]
	s_waitcnt vmcnt(18)
	v_fma_f32 v76, v76, 1.0, v184
	v_fma_f32 v77, v77, 1.0, v185
	v_fma_f32 v78, v78, 1.0, v186
	v_fma_f32 v79, v79, 1.0, v187
	v_fma_f32 v72, v72, 1.0, v188
	v_fma_f32 v73, v73, 1.0, v189
	v_fma_f32 v74, v74, 1.0, v190
	v_fma_f32 v75, v75, 1.0, v191
	v_fma_f32 v68, v68, 1.0, v192
	v_fma_f32 v69, v69, 1.0, v193
	v_fma_f32 v70, v70, 1.0, v194
	v_fma_f32 v71, v71, 1.0, v195
	v_fma_f32 v64, v64, 1.0, v196
	v_fma_f32 v65, v65, 1.0, v197
	v_fma_f32 v66, v66, 1.0, v198
	v_fma_f32 v67, v67, 1.0, v199
	s_add_u32 s84, s82, 0x90000
	s_addc_u32 s85, s83, 0
	global_load_dwordx4 v[216:219], v144, s[84:85]
	global_load_dwordx4 v[220:223], v144, s[84:85] offset:16
	global_load_dwordx4 v[224:227], v144, s[84:85] offset:512
	global_load_dwordx4 v[228:231], v144, s[84:85] offset:528
	s_add_u32 s86, s82, 0x30000
	s_addc_u32 s87, s83, 0
	global_store_dwordx4 v144, v[76:79], s[86:87] nt
	global_store_dwordx4 v144, v[72:75], s[86:87] offset:16 nt
	global_store_dwordx4 v144, v[68:71], s[86:87] offset:512 nt
	global_store_dwordx4 v144, v[64:67], s[86:87] offset:528 nt
	v_cvt_pk_bf16_f32 v236, v76, v77
	v_cvt_pk_bf16_f32 v237, v78, v79
	v_cvt_pk_bf16_f32 v238, v72, v73
	v_cvt_pk_bf16_f32 v239, v74, v75
	v_cvt_pk_bf16_f32 v240, v68, v69
	v_cvt_pk_bf16_f32 v241, v70, v71
	v_cvt_pk_bf16_f32 v242, v64, v65
	v_cvt_pk_bf16_f32 v243, v66, v67
	s_add_u32 s88, s72, 0x18000
	s_addc_u32 s89, s73, 0
	global_store_dwordx4 v145, v[236:239], s[88:89]
	global_store_dwordx4 v145, v[240:243], s[88:89] offset:256
	v_mul_f32_e32 v232, v77, v77
	v_fmac_f32_e32 v232, v76, v76
	v_mul_f32_e32 v233, v73, v73
	v_fmac_f32_e32 v233, v72, v72
	v_mul_f32_e32 v234, v69, v69
	v_fmac_f32_e32 v234, v68, v68
	v_mul_f32_e32 v235, v65, v65
	v_fmac_f32_e32 v235, v64, v64
	v_mul_f32_e32 v248, v79, v79
	v_fmac_f32_e32 v248, v78, v78
	v_mul_f32_e32 v249, v75, v75
	v_fmac_f32_e32 v249, v74, v74
	v_mul_f32_e32 v250, v71, v71
	v_fmac_f32_e32 v250, v70, v70
	v_mul_f32_e32 v251, v67, v67
	v_fmac_f32_e32 v251, v66, v66
	v_add_f32_e32 v232, v232, v248
	v_add_f32_e32 v233, v233, v249
	v_add_f32_e32 v234, v234, v250
	v_add_f32_e32 v235, v235, v251
	v_add_f32_e32 v232, v232, v233
	v_add_f32_e32 v234, v234, v235
	v_add_f32_e32 v232, v232, v234
	ds_bpermute_b32 v233, v147, v232
	s_waitcnt lgkmcnt(0)
	v_add_f32_e32 v232, v232, v233
	ds_bpermute_b32 v233, v148, v232
	s_waitcnt lgkmcnt(0)
	v_add_f32_e32 v232, v232, v233
	s_and_saveexec_b64 s[6:7], s[8:9]
	global_atomic_add_f32 v146, v232, s[2:3] offset:192
	s_mov_b64 exec, s[6:7]
	s_waitcnt vmcnt(18)
; __device__ __forceinline__ unsigned cvt_pk_bf16(float lo, float hi) { f32x2_t v = {lo, hi}; bf16x2_t b = __builtin_convertvector(v, bf16x2_t); return __builtin_bit_cast(unsigned, b); }
;     __device__ __forceinline__ void operator()(const Acc& acc, const Unit& u, int wr, int wc, int fr, int fq) const {
;         const int row0 = u.pm * BM + wr * 64 + fr, col0 = u.pn * BM + wc * 32 + 8 * fq;
; #pragma unroll
;         for (int ai = 0; ai < 2; ++ai)
; #pragma unroll
;             for (int m = 0; m < 4; ++m) {
;                 const int row = row0 + ai * HALF + m * 16; float sq = 0.f;
; #pragma unroll
;                 for (int bj = 0; bj < 2; ++bj) {
;                     const size_t off = (size_t)row * DM + col0 + bj * HALF;
;                     const f32x4 b0 = *(const f32x4*)(base + off), b1 = *(const f32x4*)(base + off + 4);
;                     const f32x4 x0 = b0 + acc[ai][bj][m][0] * alpha, x1 = b1 + acc[ai][bj][m][1] * alpha;
;                     __builtin_nontemporal_store(x0, (f32x4*)(out + off)); __builtin_nontemporal_store(x1, (f32x4*)(out + off + 4));
;                     sq += (x0[0] * x0[0] + x0[1] * x0[1]) + (x0[2] * x0[2] + x0[3] * x0[3]) + (x1[0] * x1[0] + x1[1] * x1[1]) + (x1[2] * x1[2] + x1[3] * x1[3]);
;                     if (xb) { u32x4 w; w.x = cvt_pk_bf16(x0[0], x0[1]); w.y = cvt_pk_bf16(x0[2], x0[3]); w.z = cvt_pk_bf16(x1[0], x1[1]); w.w = cvt_pk_bf16(x1[2], x1[3]); *(u32x4*)(xb + off) = w; }
;                 }
;                 sq += __shfl_xor(sq, 16); sq += __shfl_xor(sq, 32);
;                 if (fq == 0) unsafeAtomicAdd(ss + row, sq);
;             }
	v_fma_f32 v60, v60, 1.0, v200
	v_fma_f32 v61, v61, 1.0, v201
	v_fma_f32 v62, v62, 1.0, v202
	v_fma_f32 v63, v63, 1.0, v203
	v_fma_f32 v56, v56, 1.0, v204
	v_fma_f32 v57, v57, 1.0, v205
	v_fma_f32 v58, v58, 1.0, v206
	v_fma_f32 v59, v59, 1.0, v207
	v_fma_f32 v52, v52, 1.0, v208
	v_fma_f32 v53, v53, 1.0, v209
	v_fma_f32 v54, v54, 1.0, v210
	v_fma_f32 v55, v55, 1.0, v211
	v_fma_f32 v48, v48, 1.0, v212
	v_fma_f32 v49, v49, 1.0, v213
	v_fma_f32 v50, v50, 1.0, v214
	v_fma_f32 v51, v51, 1.0, v215
	s_add_u32 s84, s82, 0xa0000
	s_addc_u32 s85, s83, 0
	global_load_dwordx4 v[184:187], v144, s[84:85]
	global_load_dwordx4 v[188:191], v144, s[84:85] offset:16
	global_load_dwordx4 v[192:195], v144, s[84:85] offset:512
	global_load_dwordx4 v[196:199], v144, s[84:85] offset:528
	s_add_u32 s86, s82, 0x80000
	s_addc_u32 s87, s83, 0
	global_store_dwordx4 v144, v[60:63], s[86:87] nt
	global_store_dwordx4 v144, v[56:59], s[86:87] offset:16 nt
	global_store_dwordx4 v144, v[52:55], s[86:87] offset:512 nt
	global_store_dwordx4 v144, v[48:51], s[86:87] offset:528 nt
	v_cvt_pk_bf16_f32 v236, v60, v61
	v_cvt_pk_bf16_f32 v237, v62, v63
	v_cvt_pk_bf16_f32 v238, v56, v57
	v_cvt_pk_bf16_f32 v239, v58, v59
	v_cvt_pk_bf16_f32 v240, v52, v53
	v_cvt_pk_bf16_f32 v241, v54, v55
	v_cvt_pk_bf16_f32 v242, v48, v49
	v_cvt_pk_bf16_f32 v243, v50, v51
	s_add_u32 s88, s72, 0x40000
	s_addc_u32 s89, s73, 0
	global_store_dwordx4 v145, v[236:239], s[88:89]
	global_store_dwordx4 v145, v[240:243], s[88:89] offset:256
	v_mul_f32_e32 v232, v61, v61
	v_fmac_f32_e32 v232, v60, v60
	v_mul_f32_e32 v233, v57, v57
	v_fmac_f32_e32 v233, v56, v56
	v_mul_f32_e32 v234, v53, v53
	v_fmac_f32_e32 v234, v52, v52
	v_mul_f32_e32 v235, v49, v49
	v_fmac_f32_e32 v235, v48, v48
	v_mul_f32_e32 v248, v63, v63
	v_fmac_f32_e32 v248, v62, v62
	v_mul_f32_e32 v249, v59, v59
	v_fmac_f32_e32 v249, v58, v58
	v_mul_f32_e32 v250, v55, v55
	v_fmac_f32_e32 v250, v54, v54
	v_mul_f32_e32 v251, v51, v51
	v_fmac_f32_e32 v251, v50, v50
	v_add_f32_e32 v232, v232, v248
	v_add_f32_e32 v233, v233, v249
	v_add_f32_e32 v234, v234, v250
	v_add_f32_e32 v235, v235, v251
	v_add_f32_e32 v232, v232, v233
	v_add_f32_e32 v234, v234, v235
	v_add_f32_e32 v232, v232, v234
	ds_bpermute_b32 v233, v147, v232
	s_waitcnt lgkmcnt(0)
	v_add_f32_e32 v232, v232, v233
	ds_bpermute_b32 v233, v148, v232
	s_waitcnt lgkmcnt(0)
	v_add_f32_e32 v232, v232, v233
	s_and_saveexec_b64 s[6:7], s[8:9]
	global_atomic_add_f32 v146, v232, s[2:3] offset:512
	s_mov_b64 exec, s[6:7]
	s_waitcnt vmcnt(18)
	v_fma_f32 v44, v44, 1.0, v216
	v_fma_f32 v45, v45, 1.0, v217
	v_fma_f32 v46, v46, 1.0, v218
	v_fma_f32 v47, v47, 1.0, v219
	v_fma_f32 v40, v40, 1.0, v220
	v_fma_f32 v41, v41, 1.0, v221
	v_fma_f32 v42, v42, 1.0, v222
	v_fma_f32 v43, v43, 1.0, v223
	v_fma_f32 v36, v36, 1.0, v224
	v_fma_f32 v37, v37, 1.0, v225
	v_fma_f32 v38, v38, 1.0, v226
	v_fma_f32 v39, v39, 1.0, v227
	v_fma_f32 v32, v32, 1.0, v228
	v_fma_f32 v33, v33, 1.0, v229
	v_fma_f32 v34, v34, 1.0, v230
	v_fma_f32 v35, v35, 1.0, v231
	s_add_u32 s84, s82, 0xb0000
	s_addc_u32 s85, s83, 0
	global_load_dwordx4 v[200:203], v144, s[84:85]
	global_load_dwordx4 v[204:207], v144, s[84:85] offset:16
	global_load_dwordx4 v[208:211], v144, s[84:85] offset:512
	global_load_dwordx4 v[212:215], v144, s[84:85] offset:528
	s_add_u32 s86, s82, 0x90000
	s_addc_u32 s87, s83, 0
	global_store_dwordx4 v144, v[44:47], s[86:87] nt
	global_store_dwordx4 v144, v[40:43], s[86:87] offset:16 nt
	global_store_dwordx4 v144, v[36:39], s[86:87] offset:512 nt
	global_store_dwordx4 v144, v[32:35], s[86:87] offset:528 nt
	v_cvt_pk_bf16_f32 v236, v44, v45
	v_cvt_pk_bf16_f32 v237, v46, v47
	v_cvt_pk_bf16_f32 v238, v40, v41
	v_cvt_pk_bf16_f32 v239, v42, v43
	v_cvt_pk_bf16_f32 v240, v36, v37
	v_cvt_pk_bf16_f32 v241, v38, v39
	v_cvt_pk_bf16_f32 v242, v32, v33
	v_cvt_pk_bf16_f32 v243, v34, v35
	s_add_u32 s88, s72, 0x48000
	s_addc_u32 s89, s73, 0
	global_store_dwordx4 v145, v[236:239], s[88:89]
	global_store_dwordx4 v145, v[240:243], s[88:89] offset:256
	v_mul_f32_e32 v232, v45, v45
	v_fmac_f32_e32 v232, v44, v44
	v_mul_f32_e32 v233, v41, v41
	v_fmac_f32_e32 v233, v40, v40
	v_mul_f32_e32 v234, v37, v37
	v_fmac_f32_e32 v234, v36, v36
	v_mul_f32_e32 v235, v33, v33
	v_fmac_f32_e32 v235, v32, v32
	v_mul_f32_e32 v248, v47, v47
	v_fmac_f32_e32 v248, v46, v46
	v_mul_f32_e32 v249, v43, v43
	v_fmac_f32_e32 v249, v42, v42
	v_mul_f32_e32 v250, v39, v39
	v_fmac_f32_e32 v250, v38, v38
	v_mul_f32_e32 v251, v35, v35
	v_fmac_f32_e32 v251, v34, v34
	v_add_f32_e32 v232, v232, v248
	v_add_f32_e32 v233, v233, v249
	v_add_f32_e32 v234, v234, v250
	v_add_f32_e32 v235, v235, v251
	v_add_f32_e32 v232, v232, v233
	v_add_f32_e32 v234, v234, v235
	v_add_f32_e32 v232, v232, v234
	ds_bpermute_b32 v233, v147, v232
	s_waitcnt lgkmcnt(0)
; __device__ __forceinline__ unsigned cvt_pk_bf16(float lo, float hi) { f32x2_t v = {lo, hi}; bf16x2_t b = __builtin_convertvector(v, bf16x2_t); return __builtin_bit_cast(unsigned, b); }
;     __device__ __forceinline__ void operator()(const Acc& acc, const Unit& u, int wr, int wc, int fr, int fq) const {
;         const int row0 = u.pm * BM + wr * 64 + fr, col0 = u.pn * BM + wc * 32 + 8 * fq;
; #pragma unroll
;         for (int ai = 0; ai < 2; ++ai)
; #pragma unroll
;             for (int m = 0; m < 4; ++m) {
;                 const int row = row0 + ai * HALF + m * 16; float sq = 0.f;
; #pragma unroll
;                 for (int bj = 0; bj < 2; ++bj) {
;                     const size_t off = (size_t)row * DM + col0 + bj * HALF;
;                     const f32x4 b0 = *(const f32x4*)(base + off), b1 = *(const f32x4*)(base + off + 4);
;                     const f32x4 x0 = b0 + acc[ai][bj][m][0] * alpha, x1 = b1 + acc[ai][bj][m][1] * alpha;
;                     __builtin_nontemporal_store(x0, (f32x4*)(out + off)); __builtin_nontemporal_store(x1, (f32x4*)(out + off + 4));
;                     sq += (x0[0] * x0[0] + x0[1] * x0[1]) + (x0[2] * x0[2] + x0[3] * x0[3]) + (x1[0] * x1[0] + x1[1] * x1[1]) + (x1[2] * x1[2] + x1[3] * x1[3]);
;                     if (xb) { u32x4 w; w.x = cvt_pk_bf16(x0[0], x0[1]); w.y = cvt_pk_bf16(x0[2], x0[3]); w.z = cvt_pk_bf16(x1[0], x1[1]); w.w = cvt_pk_bf16(x1[2], x1[3]); *(u32x4*)(xb + off) = w; }
;                 }
;                 sq += __shfl_xor(sq, 16); sq += __shfl_xor(sq, 32);
;                 if (fq == 0) unsafeAtomicAdd(ss + row, sq);
;             }
	v_add_f32_e32 v232, v232, v233
	ds_bpermute_b32 v233, v148, v232
	s_waitcnt lgkmcnt(0)
	v_add_f32_e32 v232, v232, v233
	s_and_saveexec_b64 s[6:7], s[8:9]
	global_atomic_add_f32 v146, v232, s[2:3] offset:576
	s_mov_b64 exec, s[6:7]
	s_waitcnt vmcnt(18)
	v_fma_f32 v28, v28, 1.0, v184
	v_fma_f32 v29, v29, 1.0, v185
	v_fma_f32 v30, v30, 1.0, v186
	v_fma_f32 v31, v31, 1.0, v187
	v_fma_f32 v24, v24, 1.0, v188
	v_fma_f32 v25, v25, 1.0, v189
	v_fma_f32 v26, v26, 1.0, v190
	v_fma_f32 v27, v27, 1.0, v191
	v_fma_f32 v20, v20, 1.0, v192
	v_fma_f32 v21, v21, 1.0, v193
	v_fma_f32 v22, v22, 1.0, v194
	v_fma_f32 v23, v23, 1.0, v195
	v_fma_f32 v16, v16, 1.0, v196
	v_fma_f32 v17, v17, 1.0, v197
	v_fma_f32 v18, v18, 1.0, v198
	v_fma_f32 v19, v19, 1.0, v199
	s_add_u32 s86, s82, 0xa0000
	s_addc_u32 s87, s83, 0
	global_store_dwordx4 v144, v[28:31], s[86:87] nt
	global_store_dwordx4 v144, v[24:27], s[86:87] offset:16 nt
	global_store_dwordx4 v144, v[20:23], s[86:87] offset:512 nt
	global_store_dwordx4 v144, v[16:19], s[86:87] offset:528 nt
	v_cvt_pk_bf16_f32 v236, v28, v29
	v_cvt_pk_bf16_f32 v237, v30, v31
	v_cvt_pk_bf16_f32 v238, v24, v25
	v_cvt_pk_bf16_f32 v239, v26, v27
	v_cvt_pk_bf16_f32 v240, v20, v21
	v_cvt_pk_bf16_f32 v241, v22, v23
	v_cvt_pk_bf16_f32 v242, v16, v17
	v_cvt_pk_bf16_f32 v243, v18, v19
	s_add_u32 s88, s72, 0x50000
	s_addc_u32 s89, s73, 0
	global_store_dwordx4 v145, v[236:239], s[88:89]
	global_store_dwordx4 v145, v[240:243], s[88:89] offset:256
	v_mul_f32_e32 v232, v29, v29
	v_fmac_f32_e32 v232, v28, v28
	v_mul_f32_e32 v233, v25, v25
	v_fmac_f32_e32 v233, v24, v24
	v_mul_f32_e32 v234, v21, v21
	v_fmac_f32_e32 v234, v20, v20
	v_mul_f32_e32 v235, v17, v17
	v_fmac_f32_e32 v235, v16, v16
	v_mul_f32_e32 v248, v31, v31
	v_fmac_f32_e32 v248, v30, v30
	v_mul_f32_e32 v249, v27, v27
	v_fmac_f32_e32 v249, v26, v26
	v_mul_f32_e32 v250, v23, v23
	v_fmac_f32_e32 v250, v22, v22
	v_mul_f32_e32 v251, v19, v19
	v_fmac_f32_e32 v251, v18, v18
	v_add_f32_e32 v232, v232, v248
	v_add_f32_e32 v233, v233, v249
	v_add_f32_e32 v234, v234, v250
	v_add_f32_e32 v235, v235, v251
	v_add_f32_e32 v232, v232, v233
	v_add_f32_e32 v234, v234, v235
	v_add_f32_e32 v232, v232, v234
	ds_bpermute_b32 v233, v147, v232
	s_waitcnt lgkmcnt(0)
	v_add_f32_e32 v232, v232, v233
	ds_bpermute_b32 v233, v148, v232
	s_waitcnt lgkmcnt(0)
	v_add_f32_e32 v232, v232, v233
	s_and_saveexec_b64 s[6:7], s[8:9]
	global_atomic_add_f32 v146, v232, s[2:3] offset:640
	s_mov_b64 exec, s[6:7]
	s_waitcnt vmcnt(14)
	v_fma_f32 v12, v12, 1.0, v200
	v_fma_f32 v13, v13, 1.0, v201
	v_fma_f32 v14, v14, 1.0, v202
	v_fma_f32 v15, v15, 1.0, v203
	v_fma_f32 v8, v8, 1.0, v204
	v_fma_f32 v9, v9, 1.0, v205
	v_fma_f32 v10, v10, 1.0, v206
	v_fma_f32 v11, v11, 1.0, v207
	v_fma_f32 v4, v4, 1.0, v208
	v_fma_f32 v5, v5, 1.0, v209
	v_fma_f32 v6, v6, 1.0, v210
	v_fma_f32 v7, v7, 1.0, v211
	v_fma_f32 v0, v0, 1.0, v212
	v_fma_f32 v1, v1, 1.0, v213
	v_fma_f32 v2, v2, 1.0, v214
	v_fma_f32 v3, v3, 1.0, v215
	s_add_u32 s86, s82, 0xb0000
	s_addc_u32 s87, s83, 0
	global_store_dwordx4 v144, v[12:15], s[86:87] nt
	global_store_dwordx4 v144, v[8:11], s[86:87] offset:16 nt
	global_store_dwordx4 v144, v[4:7], s[86:87] offset:512 nt
	global_store_dwordx4 v144, v[0:3], s[86:87] offset:528 nt
	v_cvt_pk_bf16_f32 v236, v12, v13
	v_cvt_pk_bf16_f32 v237, v14, v15
	v_cvt_pk_bf16_f32 v238, v8, v9
	v_cvt_pk_bf16_f32 v239, v10, v11
	v_cvt_pk_bf16_f32 v240, v4, v5
	v_cvt_pk_bf16_f32 v241, v6, v7
	v_cvt_pk_bf16_f32 v242, v0, v1
	v_cvt_pk_bf16_f32 v243, v2, v3
	s_add_u32 s88, s72, 0x58000
	s_addc_u32 s89, s73, 0
	global_store_dwordx4 v145, v[236:239], s[88:89]
	global_store_dwordx4 v145, v[240:243], s[88:89] offset:256
	v_mul_f32_e32 v232, v13, v13
	v_fmac_f32_e32 v232, v12, v12
	v_mul_f32_e32 v233, v9, v9
	v_fmac_f32_e32 v233, v8, v8
	v_mul_f32_e32 v234, v5, v5
	v_fmac_f32_e32 v234, v4, v4
	v_mul_f32_e32 v235, v1, v1
	v_fmac_f32_e32 v235, v0, v0
	v_mul_f32_e32 v248, v15, v15
	v_fmac_f32_e32 v248, v14, v14
	v_mul_f32_e32 v249, v11, v11
	v_fmac_f32_e32 v249, v10, v10
	v_mul_f32_e32 v250, v7, v7
	v_fmac_f32_e32 v250, v6, v6
	v_mul_f32_e32 v251, v3, v3
	v_fmac_f32_e32 v251, v2, v2
	v_add_f32_e32 v232, v232, v248
	v_add_f32_e32 v233, v233, v249
	v_add_f32_e32 v234, v234, v250
	v_add_f32_e32 v235, v235, v251
	v_add_f32_e32 v232, v232, v233
	v_add_f32_e32 v234, v234, v235
	v_add_f32_e32 v232, v232, v234
	ds_bpermute_b32 v233, v147, v232
	s_waitcnt lgkmcnt(0)
	v_add_f32_e32 v232, v232, v233
	ds_bpermute_b32 v233, v148, v232
	s_waitcnt lgkmcnt(0)
	v_add_f32_e32 v232, v232, v233
	s_and_saveexec_b64 s[6:7], s[8:9]
	global_atomic_add_f32 v146, v232, s[2:3] offset:704
	s_mov_b64 exec, s[6:7]
	s_branch .Lg6_epi_done

; #define PG8_BAR __builtin_amdgcn_s_barrier()
; template <class Epi>
; __device__ __forceinline__ void gemm_phase(LAS unsigned char* lds, const Gemm g, const StaticOrder& S, const Epi& E) {
;     ...
;         if (!has_next) break;
; #pragma unroll
;         for (int a = 0; a < 2; ++a)
; #pragma unroll
;             for (int b = 0; b < 2; ++b)
; #pragma unroll
;                 for (int m = 0; m < 4; ++m)
; #pragma unroll
;                     for (int n = 0; n < 2; ++n) acc[a][b][m][n] = (f32x4){0.f, 0.f, 0.f, 0.f};
;         cur = nxt; cA = nA; cB = nB; ++ui;
;         if (wr == 1) PG8_BAR;
.Lg6_epi_done:
	s_andn2_b64 vcc, exec, s[10:11]
	s_mov_b64 s[6:7], -1
	s_cbranch_vccnz .LBB0_1226
	s_andn2_b64 vcc, exec, s[14:15]
	s_cbranch_vccnz .LBB0_1225
	s_barrier
	s_branch .LBB0_1225
